# ROT2c: loop-edge SALU block placed behind the last LDS-DMA load of the previous load segment, directly in front of its closing waits (best otherwise unchanged)
# baseline (speedup 1.0000x reference)
.Lz0_0_1_ret:
	s_add_i32 s49, 0, 0x18000
	s_add_i32 s50, 0, 0x1c000
	v_add_u32_e32 v156, s49, v145
	v_add_u32_e32 v175, s50, v145
	ds_read_b128 v[140:143], v156
	ds_read_b128 v[148:151], v156 offset:1024
	ds_read_b128 v[152:155], v156 offset:2048
	ds_read_b128 v[156:159], v156 offset:3072
	ds_read_b128 v[160:163], v175
	ds_read_b128 v[164:167], v175 offset:1024
	ds_read_b128 v[168:171], v175 offset:2048
	ds_read_b128 v[190:193], v175 offset:3072
	s_add_u32 s24, s24, 0x100000
	s_addc_u32 s25, s25, 0
	s_mov_b32 m0, s37
	v_lshl_add_u64 v[244:245], s[24:25], 0, v[134:135]
	ds_read_b128 v[194:197], v147 offset:32768
	ds_read_b128 v[198:201], v147 offset:33792
	ds_read_b128 v[202:205], v147 offset:34816
	ds_read_b128 v[206:209], v147 offset:35840
	ds_read_b128 v[228:231], v147 offset:36864
	ds_read_b128 v[232:235], v147 offset:37888
	ds_read_b128 v[236:239], v147 offset:38912
	ds_read_b128 v[240:243], v147 offset:39936
	global_load_lds_dwordx4 v[244:245], off
	v_lshl_add_u64 v[244:245], s[24:25], 0, v[132:133]
	s_mov_b32 m0, s38
	s_nop 0
	global_load_lds_dwordx4 v[244:245], off
	s_waitcnt vmcnt(8)
	s_waitcnt lgkmcnt(0)
	s_setprio 1
	s_barrier
	v_mfma_f32_16x16x32_bf16 v[126:129], v[140:143], v[194:197], v[126:129]
	v_mfma_f32_16x16x32_bf16 v[126:129], v[148:151], v[198:201], v[126:129]
	v_mfma_f32_16x16x32_bf16 v[118:121], v[148:151], v[206:209], v[118:121]
	v_mfma_f32_16x16x32_bf16 v[118:121], v[140:143], v[202:205], v[118:121]
	v_mfma_f32_16x16x32_bf16 v[102:105], v[140:143], v[228:231], v[102:105]
	v_mfma_f32_16x16x32_bf16 v[102:105], v[148:151], v[232:235], v[102:105]
	v_mfma_f32_16x16x32_bf16 v[86:89], v[148:151], v[240:243], v[86:89]
	v_mfma_f32_16x16x32_bf16 v[86:89], v[140:143], v[236:239], v[86:89]
	v_mfma_f32_16x16x32_bf16 v[78:81], v[152:155], v[236:239], v[78:81]
	v_mfma_f32_16x16x32_bf16 v[78:81], v[156:159], v[240:243], v[78:81]
	v_mfma_f32_16x16x32_bf16 v[94:97], v[156:159], v[232:235], v[94:97]
	v_mfma_f32_16x16x32_bf16 v[94:97], v[152:155], v[228:231], v[94:97]
	v_mfma_f32_16x16x32_bf16 v[110:113], v[152:155], v[202:205], v[110:113]
	v_mfma_f32_16x16x32_bf16 v[110:113], v[156:159], v[206:209], v[110:113]
	v_mfma_f32_16x16x32_bf16 v[122:125], v[156:159], v[198:201], v[122:125]
	v_mfma_f32_16x16x32_bf16 v[122:125], v[152:155], v[194:197], v[122:125]
	v_mfma_f32_16x16x32_bf16 v[114:117], v[160:163], v[194:197], v[114:117]
	v_mfma_f32_16x16x32_bf16 v[114:117], v[164:167], v[198:201], v[114:117]
	v_mfma_f32_16x16x32_bf16 v[98:101], v[164:167], v[206:209], v[98:101]
	v_mfma_f32_16x16x32_bf16 v[98:101], v[160:163], v[202:205], v[98:101]
	v_mfma_f32_16x16x32_bf16 v[82:85], v[160:163], v[228:231], v[82:85]
	v_mfma_f32_16x16x32_bf16 v[82:85], v[164:167], v[232:235], v[82:85]
	v_mfma_f32_16x16x32_bf16 v[70:73], v[164:167], v[240:243], v[70:73]
	v_mfma_f32_16x16x32_bf16 v[70:73], v[160:163], v[236:239], v[70:73]
	v_mfma_f32_16x16x32_bf16 v[66:69], v[168:171], v[236:239], v[66:69]
	v_mfma_f32_16x16x32_bf16 v[66:69], v[190:193], v[240:243], v[66:69]
	v_mfma_f32_16x16x32_bf16 v[74:77], v[190:193], v[232:235], v[74:77]
	v_mfma_f32_16x16x32_bf16 v[74:77], v[168:171], v[228:231], v[74:77]
	v_mfma_f32_16x16x32_bf16 v[90:93], v[168:171], v[202:205], v[90:93]
	v_mfma_f32_16x16x32_bf16 v[90:93], v[190:193], v[206:209], v[90:93]
	v_mfma_f32_16x16x32_bf16 v[106:109], v[190:193], v[198:201], v[106:109]
	v_mfma_f32_16x16x32_bf16 v[106:109], v[168:171], v[194:197], v[106:109]
	s_barrier
	s_setprio 0
	s_add_i32 s24, s49, s26
	v_lshl_add_u64 v[172:173], v[172:173], 0, s[34:35]
	s_mov_b32 m0, s24
	s_nop 0
	global_load_lds_dwordx4 v[172:173], off
	ds_read_b128 v[194:197], v147 offset:49152
	ds_read_b128 v[198:201], v147 offset:50176
	s_add_i32 m0, s24, 0x2000
	s_add_u32 s22, s22, 0x100080
	v_lshl_add_u64 v[172:173], v[178:179], 0, s[34:35]
	s_addc_u32 s23, s23, 0
	s_add_i32 s24, s50, s26
	global_load_lds_dwordx4 v[172:173], off
	ds_read_b128 v[202:205], v147 offset:51200
	ds_read_b128 v[206:209], v147 offset:52224
	v_lshl_add_u64 v[172:173], s[22:23], 0, v[0:1]
	s_mov_b32 m0, s24
	s_nop 0
	global_load_lds_dwordx4 v[172:173], off
	ds_read_b128 v[228:231], v147 offset:53248
	ds_read_b128 v[232:235], v147 offset:54272
	v_lshl_add_u64 v[172:173], s[22:23], 0, v[130:131]
	s_add_i32 m0, s24, 0x2000
	s_nop 0
	global_load_lds_dwordx4 v[172:173], off
	ds_read_b128 v[236:239], v147 offset:55296
	ds_read_b128 v[240:243], v147 offset:56320
	v_lshl_add_u64 v[172:173], v[180:181], 0, s[34:35]
	s_mov_b32 m0, s39
	s_nop 0
	global_load_lds_dwordx4 v[172:173], off
	v_lshl_add_u64 v[172:173], v[210:211], 0, s[34:35]
	s_mov_b32 m0, s40
	s_nop 0
	global_load_lds_dwordx4 v[172:173], off
	s_add_i32 s48, s48, 2
	s_add_u32 s18, s18, 0x100
	s_addc_u32 s19, s19, 0
	s_add_u32 s46, s46, 0x100
	s_addc_u32 s47, s47, 0
	s_add_u32 s22, s18, 0xfff00080
	s_addc_u32 s23, s19, -1
	s_cmp_eq_u32 s48, 60
	s_cselect_b32 s25, s9, s23
	s_cselect_b32 s24, s44, s22
	s_cselect_b32 s23, s7, s47
	s_cselect_b32 s22, s45, s46
	s_waitcnt vmcnt(8)
	s_waitcnt lgkmcnt(0)
	s_setprio 1
	s_barrier
	v_mfma_f32_16x16x32_bf16 v[62:65], v[140:143], v[194:197], v[62:65]
	v_mfma_f32_16x16x32_bf16 v[62:65], v[148:151], v[198:201], v[62:65]
	v_mfma_f32_16x16x32_bf16 v[54:57], v[148:151], v[206:209], v[54:57]
	v_mfma_f32_16x16x32_bf16 v[54:57], v[140:143], v[202:205], v[54:57]
	v_mfma_f32_16x16x32_bf16 v[38:41], v[140:143], v[228:231], v[38:41]
	v_mfma_f32_16x16x32_bf16 v[38:41], v[148:151], v[232:235], v[38:41]
	v_mfma_f32_16x16x32_bf16 v[22:25], v[148:151], v[240:243], v[22:25]
	v_mfma_f32_16x16x32_bf16 v[22:25], v[140:143], v[236:239], v[22:25]
	v_mfma_f32_16x16x32_bf16 v[14:17], v[152:155], v[236:239], v[14:17]
	v_mfma_f32_16x16x32_bf16 v[14:17], v[156:159], v[240:243], v[14:17]
	v_mfma_f32_16x16x32_bf16 v[30:33], v[156:159], v[232:235], v[30:33]
	v_mfma_f32_16x16x32_bf16 v[30:33], v[152:155], v[228:231], v[30:33]
	v_mfma_f32_16x16x32_bf16 v[46:49], v[152:155], v[202:205], v[46:49]
	v_mfma_f32_16x16x32_bf16 v[46:49], v[156:159], v[206:209], v[46:49]
	v_mfma_f32_16x16x32_bf16 v[58:61], v[156:159], v[198:201], v[58:61]
	v_mfma_f32_16x16x32_bf16 v[58:61], v[152:155], v[194:197], v[58:61]
	v_mfma_f32_16x16x32_bf16 v[50:53], v[160:163], v[194:197], v[50:53]
	v_mfma_f32_16x16x32_bf16 v[50:53], v[164:167], v[198:201], v[50:53]
	v_mfma_f32_16x16x32_bf16 v[34:37], v[164:167], v[206:209], v[34:37]
	v_mfma_f32_16x16x32_bf16 v[34:37], v[160:163], v[202:205], v[34:37]
	v_mfma_f32_16x16x32_bf16 v[18:21], v[160:163], v[228:231], v[18:21]
	v_mfma_f32_16x16x32_bf16 v[18:21], v[164:167], v[232:235], v[18:21]
	v_mfma_f32_16x16x32_bf16 v[6:9], v[164:167], v[240:243], v[6:9]
	v_mfma_f32_16x16x32_bf16 v[6:9], v[160:163], v[236:239], v[6:9]
	v_mfma_f32_16x16x32_bf16 v[2:5], v[168:171], v[236:239], v[2:5]
	v_mfma_f32_16x16x32_bf16 v[2:5], v[190:193], v[240:243], v[2:5]
	v_mfma_f32_16x16x32_bf16 v[10:13], v[190:193], v[232:235], v[10:13]
	v_mfma_f32_16x16x32_bf16 v[10:13], v[168:171], v[228:231], v[10:13]
	v_mfma_f32_16x16x32_bf16 v[26:29], v[168:171], v[202:205], v[26:29]
	v_mfma_f32_16x16x32_bf16 v[26:29], v[190:193], v[206:209], v[26:29]
	v_mfma_f32_16x16x32_bf16 v[42:45], v[190:193], v[198:201], v[42:45]
	v_mfma_f32_16x16x32_bf16 v[42:45], v[168:171], v[194:197], v[42:45]
	s_barrier
	s_setprio 0
	s_cmp_gt_u32 s48, 61
	s_cbranch_scc0 .LBB0_139
	s_and_b64 vcc, exec, s[4:5]
	s_cbranch_vccz .LBB0_142
	s_barrier

.Lz0_1_1_ret:
	s_add_i32 s53, 0, 0x18000
	s_add_i32 s54, 0, 0x1c000
	v_add_u32_e32 v158, s53, v143
	v_add_u32_e32 v175, s54, v143
	ds_read_b128 v[146:149], v158
	ds_read_b128 v[150:153], v158 offset:1024
	ds_read_b128 v[154:157], v158 offset:2048
	ds_read_b128 v[158:161], v158 offset:3072
	ds_read_b128 v[162:165], v175
	ds_read_b128 v[166:169], v175 offset:1024
	ds_read_b128 v[170:173], v175 offset:2048
	ds_read_b128 v[178:181], v175 offset:3072
	s_add_u32 s24, s24, 0x100000
	s_addc_u32 s25, s25, 0
	s_mov_b32 m0, s41
	v_lshl_add_u64 v[226:227], s[24:25], 0, v[134:135]
	ds_read_b128 v[190:193], v145 offset:32768
	ds_read_b128 v[194:197], v145 offset:33792
	ds_read_b128 v[198:201], v145 offset:34816
	ds_read_b128 v[202:205], v145 offset:35840
	ds_read_b128 v[206:209], v145 offset:36864
	ds_read_b128 v[228:231], v145 offset:37888
	ds_read_b128 v[232:235], v145 offset:38912
	ds_read_b128 v[236:239], v145 offset:39936
	global_load_lds_dwordx4 v[226:227], off
	v_lshl_add_u64 v[226:227], s[24:25], 0, v[132:133]
	s_mov_b32 m0, s42
	s_nop 0
	global_load_lds_dwordx4 v[226:227], off
	s_waitcnt vmcnt(8)
	s_waitcnt lgkmcnt(0)
	s_setprio 1
	s_barrier
	v_mfma_f32_16x16x32_bf16 v[126:129], v[146:149], v[190:193], v[126:129]
	v_mfma_f32_16x16x32_bf16 v[126:129], v[150:153], v[194:197], v[126:129]
	v_mfma_f32_16x16x32_bf16 v[118:121], v[150:153], v[202:205], v[118:121]
	v_mfma_f32_16x16x32_bf16 v[118:121], v[146:149], v[198:201], v[118:121]
	v_mfma_f32_16x16x32_bf16 v[102:105], v[146:149], v[206:209], v[102:105]
	v_mfma_f32_16x16x32_bf16 v[102:105], v[150:153], v[228:231], v[102:105]
	v_mfma_f32_16x16x32_bf16 v[86:89], v[150:153], v[236:239], v[86:89]
	v_mfma_f32_16x16x32_bf16 v[86:89], v[146:149], v[232:235], v[86:89]
	v_mfma_f32_16x16x32_bf16 v[78:81], v[154:157], v[232:235], v[78:81]
	v_mfma_f32_16x16x32_bf16 v[78:81], v[158:161], v[236:239], v[78:81]
	v_mfma_f32_16x16x32_bf16 v[94:97], v[158:161], v[228:231], v[94:97]
	v_mfma_f32_16x16x32_bf16 v[94:97], v[154:157], v[206:209], v[94:97]
	v_mfma_f32_16x16x32_bf16 v[110:113], v[154:157], v[198:201], v[110:113]
	v_mfma_f32_16x16x32_bf16 v[110:113], v[158:161], v[202:205], v[110:113]
	v_mfma_f32_16x16x32_bf16 v[122:125], v[158:161], v[194:197], v[122:125]
	v_mfma_f32_16x16x32_bf16 v[122:125], v[154:157], v[190:193], v[122:125]
	v_mfma_f32_16x16x32_bf16 v[114:117], v[162:165], v[190:193], v[114:117]
	v_mfma_f32_16x16x32_bf16 v[114:117], v[166:169], v[194:197], v[114:117]
	v_mfma_f32_16x16x32_bf16 v[98:101], v[166:169], v[202:205], v[98:101]
	v_mfma_f32_16x16x32_bf16 v[98:101], v[162:165], v[198:201], v[98:101]
	v_mfma_f32_16x16x32_bf16 v[82:85], v[162:165], v[206:209], v[82:85]
	v_mfma_f32_16x16x32_bf16 v[82:85], v[166:169], v[228:231], v[82:85]
	v_mfma_f32_16x16x32_bf16 v[70:73], v[166:169], v[236:239], v[70:73]
	v_mfma_f32_16x16x32_bf16 v[70:73], v[162:165], v[232:235], v[70:73]
	v_mfma_f32_16x16x32_bf16 v[66:69], v[170:173], v[232:235], v[66:69]
	v_mfma_f32_16x16x32_bf16 v[66:69], v[178:181], v[236:239], v[66:69]
	v_mfma_f32_16x16x32_bf16 v[74:77], v[178:181], v[228:231], v[74:77]
	v_mfma_f32_16x16x32_bf16 v[74:77], v[170:173], v[206:209], v[74:77]
	v_mfma_f32_16x16x32_bf16 v[90:93], v[170:173], v[198:201], v[90:93]
	v_mfma_f32_16x16x32_bf16 v[90:93], v[178:181], v[202:205], v[90:93]
	v_mfma_f32_16x16x32_bf16 v[106:109], v[178:181], v[194:197], v[106:109]
	v_mfma_f32_16x16x32_bf16 v[106:109], v[170:173], v[190:193], v[106:109]
	s_barrier
	s_setprio 0
	s_add_i32 s24, s53, s38
	v_lshl_add_u64 v[140:141], v[140:141], 0, s[34:35]
	s_mov_b32 m0, s24
	s_nop 0
	global_load_lds_dwordx4 v[140:141], off
	ds_read_b128 v[190:193], v145 offset:49152
	ds_read_b128 v[194:197], v145 offset:50176
	s_add_i32 m0, s24, 0x2000
	s_add_u32 s22, s22, 0x100080
	v_lshl_add_u64 v[140:141], v[186:187], 0, s[34:35]
	s_addc_u32 s23, s23, 0
	s_add_i32 s24, s54, s38
	global_load_lds_dwordx4 v[140:141], off
	ds_read_b128 v[198:201], v145 offset:51200
	ds_read_b128 v[202:205], v145 offset:52224
	v_lshl_add_u64 v[140:141], s[22:23], 0, v[0:1]
	s_mov_b32 m0, s24
	s_nop 0
	global_load_lds_dwordx4 v[140:141], off
	ds_read_b128 v[206:209], v145 offset:53248
	ds_read_b128 v[228:231], v145 offset:54272
	v_lshl_add_u64 v[140:141], s[22:23], 0, v[130:131]
	s_add_i32 m0, s24, 0x2000
	s_nop 0
	global_load_lds_dwordx4 v[140:141], off
	ds_read_b128 v[232:235], v145 offset:55296
	ds_read_b128 v[236:239], v145 offset:56320
	v_lshl_add_u64 v[140:141], v[188:189], 0, s[34:35]
	s_mov_b32 m0, s43
	s_nop 0
	global_load_lds_dwordx4 v[140:141], off
	v_lshl_add_u64 v[140:141], v[210:211], 0, s[34:35]
	s_mov_b32 m0, s44
	s_nop 0
	global_load_lds_dwordx4 v[140:141], off
	s_add_i32 s52, s52, 2
	s_add_u32 s18, s18, 0x100
	s_addc_u32 s19, s19, 0
	s_add_u32 s50, s50, 0x100
	s_addc_u32 s51, s51, 0
	s_add_u32 s22, s18, 0xfff00080
	s_addc_u32 s23, s19, -1
	s_cmp_eq_u32 s52, 60
	s_cselect_b32 s25, s9, s23
	s_cselect_b32 s24, s48, s22
	s_cselect_b32 s23, s7, s51
	s_cselect_b32 s22, s49, s50
	s_waitcnt vmcnt(8)
	s_waitcnt lgkmcnt(0)
	s_setprio 1
	s_barrier
	v_mfma_f32_16x16x32_bf16 v[62:65], v[146:149], v[190:193], v[62:65]
	v_mfma_f32_16x16x32_bf16 v[62:65], v[150:153], v[194:197], v[62:65]
	v_mfma_f32_16x16x32_bf16 v[54:57], v[150:153], v[202:205], v[54:57]
	v_mfma_f32_16x16x32_bf16 v[54:57], v[146:149], v[198:201], v[54:57]
	v_mfma_f32_16x16x32_bf16 v[38:41], v[146:149], v[206:209], v[38:41]
	v_mfma_f32_16x16x32_bf16 v[38:41], v[150:153], v[228:231], v[38:41]
	v_mfma_f32_16x16x32_bf16 v[22:25], v[150:153], v[236:239], v[22:25]
	v_mfma_f32_16x16x32_bf16 v[22:25], v[146:149], v[232:235], v[22:25]
	v_mfma_f32_16x16x32_bf16 v[14:17], v[154:157], v[232:235], v[14:17]
	v_mfma_f32_16x16x32_bf16 v[14:17], v[158:161], v[236:239], v[14:17]
	v_mfma_f32_16x16x32_bf16 v[30:33], v[158:161], v[228:231], v[30:33]
	v_mfma_f32_16x16x32_bf16 v[30:33], v[154:157], v[206:209], v[30:33]
	v_mfma_f32_16x16x32_bf16 v[46:49], v[154:157], v[198:201], v[46:49]
	v_mfma_f32_16x16x32_bf16 v[46:49], v[158:161], v[202:205], v[46:49]
	v_mfma_f32_16x16x32_bf16 v[58:61], v[158:161], v[194:197], v[58:61]
	v_mfma_f32_16x16x32_bf16 v[58:61], v[154:157], v[190:193], v[58:61]
	v_mfma_f32_16x16x32_bf16 v[50:53], v[162:165], v[190:193], v[50:53]
	v_mfma_f32_16x16x32_bf16 v[50:53], v[166:169], v[194:197], v[50:53]
	v_mfma_f32_16x16x32_bf16 v[34:37], v[166:169], v[202:205], v[34:37]
	v_mfma_f32_16x16x32_bf16 v[34:37], v[162:165], v[198:201], v[34:37]
	v_mfma_f32_16x16x32_bf16 v[18:21], v[162:165], v[206:209], v[18:21]
	v_mfma_f32_16x16x32_bf16 v[18:21], v[166:169], v[228:231], v[18:21]
	v_mfma_f32_16x16x32_bf16 v[6:9], v[166:169], v[236:239], v[6:9]
	v_mfma_f32_16x16x32_bf16 v[6:9], v[162:165], v[232:235], v[6:9]
	v_mfma_f32_16x16x32_bf16 v[2:5], v[170:173], v[232:235], v[2:5]
	v_mfma_f32_16x16x32_bf16 v[2:5], v[178:181], v[236:239], v[2:5]
	v_mfma_f32_16x16x32_bf16 v[10:13], v[178:181], v[228:231], v[10:13]
	v_mfma_f32_16x16x32_bf16 v[10:13], v[170:173], v[206:209], v[10:13]
	v_mfma_f32_16x16x32_bf16 v[26:29], v[170:173], v[198:201], v[26:29]
	v_mfma_f32_16x16x32_bf16 v[26:29], v[178:181], v[202:205], v[26:29]
	v_mfma_f32_16x16x32_bf16 v[42:45], v[178:181], v[194:197], v[42:45]
	v_mfma_f32_16x16x32_bf16 v[42:45], v[170:173], v[190:193], v[42:45]
	s_barrier
	s_setprio 0
	s_cmp_gt_u32 s52, 61
	s_cbranch_scc0 .LBB0_575
	s_and_b64 vcc, exec, s[4:5]
	s_cbranch_vccz .LBB0_578
	s_barrier

.Lz0_2_1_ret:
	s_add_i32 s53, 0, 0x18000
	s_add_i32 s54, 0, 0x1c000
	v_add_u32_e32 v158, s53, v143
	v_add_u32_e32 v175, s54, v143
	ds_read_b128 v[146:149], v158
	ds_read_b128 v[150:153], v158 offset:1024
	ds_read_b128 v[154:157], v158 offset:2048
	ds_read_b128 v[158:161], v158 offset:3072
	ds_read_b128 v[162:165], v175
	ds_read_b128 v[166:169], v175 offset:1024
	ds_read_b128 v[170:173], v175 offset:2048
	ds_read_b128 v[178:181], v175 offset:3072
	s_add_u32 s22, s22, 0x100000
	s_addc_u32 s23, s23, 0
	s_mov_b32 m0, s41
	v_lshl_add_u64 v[226:227], s[22:23], 0, v[134:135]
	ds_read_b128 v[190:193], v145 offset:32768
	ds_read_b128 v[194:197], v145 offset:33792
	ds_read_b128 v[198:201], v145 offset:34816
	ds_read_b128 v[202:205], v145 offset:35840
	ds_read_b128 v[206:209], v145 offset:36864
	ds_read_b128 v[228:231], v145 offset:37888
	ds_read_b128 v[232:235], v145 offset:38912
	ds_read_b128 v[236:239], v145 offset:39936
	global_load_lds_dwordx4 v[226:227], off
	v_lshl_add_u64 v[226:227], s[22:23], 0, v[132:133]
	s_mov_b32 m0, s42
	s_nop 0
	global_load_lds_dwordx4 v[226:227], off
	s_waitcnt vmcnt(8)
	s_waitcnt lgkmcnt(0)
	s_setprio 1
	s_barrier
	v_mfma_f32_16x16x32_bf16 v[126:129], v[146:149], v[190:193], v[126:129]
	v_mfma_f32_16x16x32_bf16 v[126:129], v[150:153], v[194:197], v[126:129]
	v_mfma_f32_16x16x32_bf16 v[110:113], v[150:153], v[202:205], v[110:113]
	v_mfma_f32_16x16x32_bf16 v[110:113], v[146:149], v[198:201], v[110:113]
	v_mfma_f32_16x16x32_bf16 v[94:97], v[146:149], v[206:209], v[94:97]
	v_mfma_f32_16x16x32_bf16 v[94:97], v[150:153], v[228:231], v[94:97]
	v_mfma_f32_16x16x32_bf16 v[78:81], v[150:153], v[236:239], v[78:81]
	v_mfma_f32_16x16x32_bf16 v[78:81], v[146:149], v[232:235], v[78:81]
	v_mfma_f32_16x16x32_bf16 v[70:73], v[154:157], v[232:235], v[70:73]
	v_mfma_f32_16x16x32_bf16 v[70:73], v[158:161], v[236:239], v[70:73]
	v_mfma_f32_16x16x32_bf16 v[86:89], v[158:161], v[228:231], v[86:89]
	v_mfma_f32_16x16x32_bf16 v[86:89], v[154:157], v[206:209], v[86:89]
	v_mfma_f32_16x16x32_bf16 v[102:105], v[154:157], v[198:201], v[102:105]
	v_mfma_f32_16x16x32_bf16 v[102:105], v[158:161], v[202:205], v[102:105]
	v_mfma_f32_16x16x32_bf16 v[118:121], v[158:161], v[194:197], v[118:121]
	v_mfma_f32_16x16x32_bf16 v[118:121], v[154:157], v[190:193], v[118:121]
	v_mfma_f32_16x16x32_bf16 v[122:125], v[162:165], v[190:193], v[122:125]
	v_mfma_f32_16x16x32_bf16 v[122:125], v[166:169], v[194:197], v[122:125]
	v_mfma_f32_16x16x32_bf16 v[106:109], v[166:169], v[202:205], v[106:109]
	v_mfma_f32_16x16x32_bf16 v[106:109], v[162:165], v[198:201], v[106:109]
	v_mfma_f32_16x16x32_bf16 v[90:93], v[162:165], v[206:209], v[90:93]
	v_mfma_f32_16x16x32_bf16 v[90:93], v[166:169], v[228:231], v[90:93]
	v_mfma_f32_16x16x32_bf16 v[74:77], v[166:169], v[236:239], v[74:77]
	v_mfma_f32_16x16x32_bf16 v[74:77], v[162:165], v[232:235], v[74:77]
	v_mfma_f32_16x16x32_bf16 v[66:69], v[170:173], v[232:235], v[66:69]
	v_mfma_f32_16x16x32_bf16 v[66:69], v[178:181], v[236:239], v[66:69]
	v_mfma_f32_16x16x32_bf16 v[82:85], v[178:181], v[228:231], v[82:85]
	v_mfma_f32_16x16x32_bf16 v[82:85], v[170:173], v[206:209], v[82:85]
	v_mfma_f32_16x16x32_bf16 v[98:101], v[170:173], v[198:201], v[98:101]
	v_mfma_f32_16x16x32_bf16 v[98:101], v[178:181], v[202:205], v[98:101]
	v_mfma_f32_16x16x32_bf16 v[114:117], v[178:181], v[194:197], v[114:117]
	v_mfma_f32_16x16x32_bf16 v[114:117], v[170:173], v[190:193], v[114:117]
	s_barrier
	s_setprio 0
	s_add_i32 s22, s53, s26
	v_lshl_add_u64 v[140:141], v[140:141], 0, s[34:35]
	s_mov_b32 m0, s22
	s_nop 0
	global_load_lds_dwordx4 v[140:141], off
	ds_read_b128 v[190:193], v145 offset:49152
	ds_read_b128 v[194:197], v145 offset:50176
	s_add_i32 m0, s22, 0x2000
	s_add_u32 s18, s18, 0x100080
	v_lshl_add_u64 v[140:141], v[186:187], 0, s[34:35]
	s_addc_u32 s19, s19, 0
	s_add_i32 s22, s54, s26
	global_load_lds_dwordx4 v[140:141], off
	ds_read_b128 v[198:201], v145 offset:51200
	ds_read_b128 v[202:205], v145 offset:52224
	v_lshl_add_u64 v[140:141], s[18:19], 0, v[0:1]
	s_mov_b32 m0, s22
	s_nop 0
	global_load_lds_dwordx4 v[140:141], off
	ds_read_b128 v[206:209], v145 offset:53248
	ds_read_b128 v[228:231], v145 offset:54272
	v_lshl_add_u64 v[140:141], s[18:19], 0, v[130:131]
	s_add_i32 m0, s22, 0x2000
	s_nop 0
	global_load_lds_dwordx4 v[140:141], off
	ds_read_b128 v[232:235], v145 offset:55296
	ds_read_b128 v[236:239], v145 offset:56320
	v_lshl_add_u64 v[140:141], v[188:189], 0, s[34:35]
	s_mov_b32 m0, s43
	s_nop 0
	global_load_lds_dwordx4 v[140:141], off
	v_lshl_add_u64 v[140:141], v[210:211], 0, s[34:35]
	s_mov_b32 m0, s44
	s_nop 0
	global_load_lds_dwordx4 v[140:141], off
	s_add_i32 s52, s52, 2
	s_add_u32 s16, s16, 0x100
	s_addc_u32 s17, s17, 0
	s_add_u32 s50, s50, 0x100
	s_addc_u32 s51, s51, 0
	s_add_u32 s18, s16, 0xfff00080
	s_addc_u32 s19, s17, -1
	s_cmp_eq_u32 s52, 60
	s_cselect_b32 s23, s7, s19
	s_cselect_b32 s22, s48, s18
	s_cselect_b32 s19, s5, s51
	s_cselect_b32 s18, s49, s50
	s_waitcnt vmcnt(8)
	s_waitcnt lgkmcnt(0)
	s_setprio 1
	s_barrier
	v_mfma_f32_16x16x32_bf16 v[62:65], v[146:149], v[190:193], v[62:65]
	v_mfma_f32_16x16x32_bf16 v[62:65], v[150:153], v[194:197], v[62:65]
	v_mfma_f32_16x16x32_bf16 v[46:49], v[150:153], v[202:205], v[46:49]
	v_mfma_f32_16x16x32_bf16 v[46:49], v[146:149], v[198:201], v[46:49]
	v_mfma_f32_16x16x32_bf16 v[30:33], v[146:149], v[206:209], v[30:33]
	v_mfma_f32_16x16x32_bf16 v[30:33], v[150:153], v[228:231], v[30:33]
	v_mfma_f32_16x16x32_bf16 v[14:17], v[150:153], v[236:239], v[14:17]
	v_mfma_f32_16x16x32_bf16 v[14:17], v[146:149], v[232:235], v[14:17]
	v_mfma_f32_16x16x32_bf16 v[6:9], v[154:157], v[232:235], v[6:9]
	v_mfma_f32_16x16x32_bf16 v[6:9], v[158:161], v[236:239], v[6:9]
	v_mfma_f32_16x16x32_bf16 v[22:25], v[158:161], v[228:231], v[22:25]
	v_mfma_f32_16x16x32_bf16 v[22:25], v[154:157], v[206:209], v[22:25]
	v_mfma_f32_16x16x32_bf16 v[38:41], v[154:157], v[198:201], v[38:41]
	v_mfma_f32_16x16x32_bf16 v[38:41], v[158:161], v[202:205], v[38:41]
	v_mfma_f32_16x16x32_bf16 v[54:57], v[158:161], v[194:197], v[54:57]
	v_mfma_f32_16x16x32_bf16 v[54:57], v[154:157], v[190:193], v[54:57]
	v_mfma_f32_16x16x32_bf16 v[58:61], v[162:165], v[190:193], v[58:61]
	v_mfma_f32_16x16x32_bf16 v[58:61], v[166:169], v[194:197], v[58:61]
	v_mfma_f32_16x16x32_bf16 v[42:45], v[166:169], v[202:205], v[42:45]
	v_mfma_f32_16x16x32_bf16 v[42:45], v[162:165], v[198:201], v[42:45]
	v_mfma_f32_16x16x32_bf16 v[26:29], v[162:165], v[206:209], v[26:29]
	v_mfma_f32_16x16x32_bf16 v[26:29], v[166:169], v[228:231], v[26:29]
	v_mfma_f32_16x16x32_bf16 v[10:13], v[166:169], v[236:239], v[10:13]
	v_mfma_f32_16x16x32_bf16 v[10:13], v[162:165], v[232:235], v[10:13]
	v_mfma_f32_16x16x32_bf16 v[2:5], v[170:173], v[232:235], v[2:5]
	v_mfma_f32_16x16x32_bf16 v[2:5], v[178:181], v[236:239], v[2:5]
	v_mfma_f32_16x16x32_bf16 v[18:21], v[178:181], v[228:231], v[18:21]
	v_mfma_f32_16x16x32_bf16 v[18:21], v[170:173], v[206:209], v[18:21]
	v_mfma_f32_16x16x32_bf16 v[34:37], v[170:173], v[198:201], v[34:37]
	v_mfma_f32_16x16x32_bf16 v[34:37], v[178:181], v[202:205], v[34:37]
	v_mfma_f32_16x16x32_bf16 v[50:53], v[178:181], v[194:197], v[50:53]
	v_mfma_f32_16x16x32_bf16 v[50:53], v[170:173], v[190:193], v[50:53]
	s_barrier
	s_setprio 0
	s_cmp_gt_u32 s52, 61
	s_cbranch_scc0 .LBB0_721
	s_and_b64 vcc, exec, s[2:3]
	s_cbranch_vccz .LBB0_724
	s_barrier

.Lz0_3_1_ret:
	s_add_i32 s49, 0, 0x18000
	s_add_i32 s50, 0, 0x1c000
	v_add_u32_e32 v158, s49, v143
	v_add_u32_e32 v175, s50, v143
	ds_read_b128 v[146:149], v158
	ds_read_b128 v[150:153], v158 offset:1024
	ds_read_b128 v[154:157], v158 offset:2048
	ds_read_b128 v[158:161], v158 offset:3072
	ds_read_b128 v[162:165], v175
	ds_read_b128 v[166:169], v175 offset:1024
	ds_read_b128 v[170:173], v175 offset:2048
	ds_read_b128 v[178:181], v175 offset:3072
	s_add_u32 s14, s22, 0x2b0000
	s_addc_u32 s15, s23, 0
	s_mov_b32 m0, s37
	v_lshl_add_u64 v[226:227], s[14:15], 0, v[134:135]
	ds_read_b128 v[190:193], v145 offset:32768
	ds_read_b128 v[194:197], v145 offset:33792
	ds_read_b128 v[198:201], v145 offset:34816
	ds_read_b128 v[202:205], v145 offset:35840
	ds_read_b128 v[206:209], v145 offset:36864
	ds_read_b128 v[228:231], v145 offset:37888
	ds_read_b128 v[232:235], v145 offset:38912
	ds_read_b128 v[236:239], v145 offset:39936
	global_load_lds_dwordx4 v[226:227], off
	v_lshl_add_u64 v[226:227], s[14:15], 0, v[132:133]
	s_mov_b32 m0, s38
	s_nop 0
	global_load_lds_dwordx4 v[226:227], off
	s_waitcnt vmcnt(8)
	s_waitcnt lgkmcnt(0)
	s_setprio 1
	s_barrier
	v_mfma_f32_16x16x32_bf16 v[126:129], v[146:149], v[190:193], v[126:129]
	v_mfma_f32_16x16x32_bf16 v[126:129], v[150:153], v[194:197], v[126:129]
	v_mfma_f32_16x16x32_bf16 v[118:121], v[150:153], v[202:205], v[118:121]
	v_mfma_f32_16x16x32_bf16 v[118:121], v[146:149], v[198:201], v[118:121]
	v_mfma_f32_16x16x32_bf16 v[102:105], v[146:149], v[206:209], v[102:105]
	v_mfma_f32_16x16x32_bf16 v[102:105], v[150:153], v[228:231], v[102:105]
	v_mfma_f32_16x16x32_bf16 v[86:89], v[150:153], v[236:239], v[86:89]
	v_mfma_f32_16x16x32_bf16 v[86:89], v[146:149], v[232:235], v[86:89]
	v_mfma_f32_16x16x32_bf16 v[78:81], v[154:157], v[232:235], v[78:81]
	v_mfma_f32_16x16x32_bf16 v[78:81], v[158:161], v[236:239], v[78:81]
	v_mfma_f32_16x16x32_bf16 v[94:97], v[158:161], v[228:231], v[94:97]
	v_mfma_f32_16x16x32_bf16 v[94:97], v[154:157], v[206:209], v[94:97]
	v_mfma_f32_16x16x32_bf16 v[110:113], v[154:157], v[198:201], v[110:113]
	v_mfma_f32_16x16x32_bf16 v[110:113], v[158:161], v[202:205], v[110:113]
	v_mfma_f32_16x16x32_bf16 v[122:125], v[158:161], v[194:197], v[122:125]
	v_mfma_f32_16x16x32_bf16 v[122:125], v[154:157], v[190:193], v[122:125]
	v_mfma_f32_16x16x32_bf16 v[114:117], v[162:165], v[190:193], v[114:117]
	v_mfma_f32_16x16x32_bf16 v[114:117], v[166:169], v[194:197], v[114:117]
	v_mfma_f32_16x16x32_bf16 v[98:101], v[166:169], v[202:205], v[98:101]
	v_mfma_f32_16x16x32_bf16 v[98:101], v[162:165], v[198:201], v[98:101]
	v_mfma_f32_16x16x32_bf16 v[82:85], v[162:165], v[206:209], v[82:85]
	v_mfma_f32_16x16x32_bf16 v[82:85], v[166:169], v[228:231], v[82:85]
	v_mfma_f32_16x16x32_bf16 v[70:73], v[166:169], v[236:239], v[70:73]
	v_mfma_f32_16x16x32_bf16 v[70:73], v[162:165], v[232:235], v[70:73]
	v_mfma_f32_16x16x32_bf16 v[66:69], v[170:173], v[232:235], v[66:69]
	v_mfma_f32_16x16x32_bf16 v[66:69], v[178:181], v[236:239], v[66:69]
	v_mfma_f32_16x16x32_bf16 v[74:77], v[178:181], v[228:231], v[74:77]
	v_mfma_f32_16x16x32_bf16 v[74:77], v[170:173], v[206:209], v[74:77]
	v_mfma_f32_16x16x32_bf16 v[90:93], v[170:173], v[198:201], v[90:93]
	v_mfma_f32_16x16x32_bf16 v[90:93], v[178:181], v[202:205], v[90:93]
	v_mfma_f32_16x16x32_bf16 v[106:109], v[178:181], v[194:197], v[106:109]
	v_mfma_f32_16x16x32_bf16 v[106:109], v[170:173], v[190:193], v[106:109]
	s_barrier
	s_setprio 0
	s_add_i32 s14, s49, s26
	v_lshl_add_u64 v[140:141], v[140:141], 0, s[34:35]
	s_mov_b32 m0, s14
	s_nop 0
	global_load_lds_dwordx4 v[140:141], off
	ds_read_b128 v[190:193], v145 offset:49152
	ds_read_b128 v[194:197], v145 offset:50176
	s_add_i32 m0, s14, 0x2000
	s_add_u32 s14, s18, 0x2b0080
	v_lshl_add_u64 v[140:141], v[186:187], 0, s[34:35]
	s_addc_u32 s15, s19, 0
	s_add_i32 s18, s50, s26
	global_load_lds_dwordx4 v[140:141], off
	ds_read_b128 v[198:201], v145 offset:51200
	ds_read_b128 v[202:205], v145 offset:52224
	v_lshl_add_u64 v[140:141], s[14:15], 0, v[0:1]
	s_mov_b32 m0, s18
	s_nop 0
	global_load_lds_dwordx4 v[140:141], off
	ds_read_b128 v[206:209], v145 offset:53248
	ds_read_b128 v[228:231], v145 offset:54272
	v_lshl_add_u64 v[140:141], s[14:15], 0, v[130:131]
	s_add_i32 m0, s18, 0x2000
	s_nop 0
	global_load_lds_dwordx4 v[140:141], off
	ds_read_b128 v[232:235], v145 offset:55296
	ds_read_b128 v[236:239], v145 offset:56320
	v_lshl_add_u64 v[140:141], v[188:189], 0, s[34:35]
	s_mov_b32 m0, s39
	s_nop 0
	global_load_lds_dwordx4 v[140:141], off
	v_lshl_add_u64 v[140:141], v[210:211], 0, s[34:35]
	s_mov_b32 m0, s40
	s_nop 0
	global_load_lds_dwordx4 v[140:141], off
	s_add_i32 s48, s48, 2
	s_add_u32 s46, s46, 0x100
	s_addc_u32 s47, s47, 0
	s_mov_b64 s[14:15], s[16:17]
	s_add_u32 s16, s14, 0x100
	s_addc_u32 s17, s15, 0
	s_cmpk_eq_i32 s48, 0xa8
	s_cselect_b32 s23, s5, s17
	s_cselect_b32 s22, s4, s16
	s_cselect_b32 s19, s9, s47
	s_cselect_b32 s18, s8, s46
	s_waitcnt vmcnt(8)
	s_waitcnt lgkmcnt(0)
	s_setprio 1
	s_barrier
	v_mfma_f32_16x16x32_bf16 v[62:65], v[146:149], v[190:193], v[62:65]
	v_mfma_f32_16x16x32_bf16 v[62:65], v[150:153], v[194:197], v[62:65]
	v_mfma_f32_16x16x32_bf16 v[54:57], v[150:153], v[202:205], v[54:57]
	v_mfma_f32_16x16x32_bf16 v[54:57], v[146:149], v[198:201], v[54:57]
	v_mfma_f32_16x16x32_bf16 v[38:41], v[146:149], v[206:209], v[38:41]
	v_mfma_f32_16x16x32_bf16 v[38:41], v[150:153], v[228:231], v[38:41]
	v_mfma_f32_16x16x32_bf16 v[22:25], v[150:153], v[236:239], v[22:25]
	v_mfma_f32_16x16x32_bf16 v[22:25], v[146:149], v[232:235], v[22:25]
	v_mfma_f32_16x16x32_bf16 v[14:17], v[154:157], v[232:235], v[14:17]
	v_mfma_f32_16x16x32_bf16 v[14:17], v[158:161], v[236:239], v[14:17]
	v_mfma_f32_16x16x32_bf16 v[30:33], v[158:161], v[228:231], v[30:33]
	v_mfma_f32_16x16x32_bf16 v[30:33], v[154:157], v[206:209], v[30:33]
	v_mfma_f32_16x16x32_bf16 v[46:49], v[154:157], v[198:201], v[46:49]
	v_mfma_f32_16x16x32_bf16 v[46:49], v[158:161], v[202:205], v[46:49]
	v_mfma_f32_16x16x32_bf16 v[58:61], v[158:161], v[194:197], v[58:61]
	v_mfma_f32_16x16x32_bf16 v[58:61], v[154:157], v[190:193], v[58:61]
	v_mfma_f32_16x16x32_bf16 v[50:53], v[162:165], v[190:193], v[50:53]
	v_mfma_f32_16x16x32_bf16 v[50:53], v[166:169], v[194:197], v[50:53]
	v_mfma_f32_16x16x32_bf16 v[34:37], v[166:169], v[202:205], v[34:37]
	v_mfma_f32_16x16x32_bf16 v[34:37], v[162:165], v[198:201], v[34:37]
	v_mfma_f32_16x16x32_bf16 v[18:21], v[162:165], v[206:209], v[18:21]
	v_mfma_f32_16x16x32_bf16 v[18:21], v[166:169], v[228:231], v[18:21]
	v_mfma_f32_16x16x32_bf16 v[6:9], v[166:169], v[236:239], v[6:9]
	v_mfma_f32_16x16x32_bf16 v[6:9], v[162:165], v[232:235], v[6:9]
	v_mfma_f32_16x16x32_bf16 v[2:5], v[170:173], v[232:235], v[2:5]
	v_mfma_f32_16x16x32_bf16 v[2:5], v[178:181], v[236:239], v[2:5]
	v_mfma_f32_16x16x32_bf16 v[10:13], v[178:181], v[228:231], v[10:13]
	v_mfma_f32_16x16x32_bf16 v[10:13], v[170:173], v[206:209], v[10:13]
	v_mfma_f32_16x16x32_bf16 v[26:29], v[170:173], v[198:201], v[26:29]
	v_mfma_f32_16x16x32_bf16 v[26:29], v[178:181], v[202:205], v[26:29]
	v_mfma_f32_16x16x32_bf16 v[42:45], v[178:181], v[194:197], v[42:45]
	v_mfma_f32_16x16x32_bf16 v[42:45], v[170:173], v[190:193], v[42:45]
	s_barrier
	s_setprio 0
	s_cmpk_gt_u32 s48, 0xa9
	s_cbranch_scc0 .LBB0_805
	s_and_b64 vcc, exec, s[6:7]
	s_cbranch_vccz .LBB0_808
	s_barrier
